# v40 plus inverted wave priorities in the two 192-row (load-bound) K-loops: load-section wave at prio 1, MFMA-section wave at prio 0, mid-run flips removed
# speedup vs baseline: 1.0015x; 1.0015x over previous
; #define PG8_STAGE(bufoff, gbase, voff) do { _Pragma("unroll") for (int _i = 0; _i < 2; ++_i) \
;         __builtin_amdgcn_global_load_lds((const unsigned*)((const char*)(gbase) + (voff)[_i]), (LAS unsigned*)(lds + (bufoff) + ldsw + _i * 8192), 16, 0, 0); } while (0)
; #define PG8_LDA(dst, b, h) do { _Pragma("unroll") for (int m = 0; m < NM; ++m) _Pragma("unroll") for (int k = 0; k < 2; ++k) dst[m][k] = *(const LAS bf16x8*)(lds + PG8_SA(b, h) + aoff + m * 2048 + k * 1024); } while (0)
; #define PG8_MMA(ai, bj, At, Bt) do { __builtin_amdgcn_s_setprio(1); _Pragma("unroll") for (int m = 0; m < NM; ++m) _Pragma("unroll") for (int n = 0; n < 2; ++n) _Pragma("unroll") for (int k = 0; k < 2; ++k) \
;         acc[ai][bj][m][n] = __builtin_amdgcn_mfma_f32_16x16x32_bf16(Bt[n][k], At[m][k], acc[ai][bj][m][n], 0, 0, 0); __builtin_amdgcn_s_setprio(0); } while (0)
; #define PG8_WAIT_V(n) asm volatile("s_waitcnt vmcnt(" #n ")" ::: "memory")
; #define PG8_WAIT_L(n) asm volatile("s_waitcnt lgkmcnt(" #n ")" ::: "memory")
; #define PG8_BAR __builtin_amdgcn_s_barrier()
; #define PG8_SCHED __builtin_amdgcn_sched_barrier(0)
;     ...
;             PG8_WAIT_V(8); PG8_WAIT_L(0); PG8_BAR; PG8_MMA(0, 0, At, B0); PG8_MMA(0, 1, At, B1); PG8_BAR; PG8_SCHED;
;             PG8_LDA(At, 0, 1); PG8_STAGE(PG8_SB(0, 0), b2, voffB); PG8_STAGE(PG8_SB(0, 1), b2 + hstepB, voffB); PG8_STAGE(PG8_SA(0, 0), a2, voffA);
.Lnm3o_done0:
	s_waitcnt lgkmcnt(0)
	s_setprio 0
	s_barrier
	v_mfma_f32_16x16x32_bf16 v[110:113], v[90:93], v[130:133], v[110:113]
	v_mfma_f32_16x16x32_bf16 v[106:109], v[98:101], v[130:133], v[106:109]
	v_mfma_f32_16x16x32_bf16 v[78:81], v[90:93], v[138:141], v[78:81]
	v_mfma_f32_16x16x32_bf16 v[74:77], v[98:101], v[138:141], v[74:77]
	v_mfma_f32_16x16x32_bf16 v[62:65], v[90:93], v[156:159], v[62:65]
	v_mfma_f32_16x16x32_bf16 v[58:61], v[98:101], v[156:159], v[58:61]
	v_mfma_f32_16x16x32_bf16 v[110:113], v[94:97], v[134:137], v[110:113]
	v_mfma_f32_16x16x32_bf16 v[106:109], v[102:105], v[134:137], v[106:109]
	v_mfma_f32_16x16x32_bf16 v[78:81], v[94:97], v[152:155], v[78:81]
	v_mfma_f32_16x16x32_bf16 v[74:77], v[102:105], v[152:155], v[74:77]
	v_mfma_f32_16x16x32_bf16 v[62:65], v[94:97], v[160:163], v[62:65]
	v_mfma_f32_16x16x32_bf16 v[58:61], v[102:105], v[160:163], v[58:61]
	v_mfma_f32_16x16x32_bf16 v[86:89], v[114:117], v[130:133], v[86:89]
	v_mfma_f32_16x16x32_bf16 v[82:85], v[122:125], v[130:133], v[82:85]
	v_mfma_f32_16x16x32_bf16 v[70:73], v[114:117], v[138:141], v[70:73]
	v_mfma_f32_16x16x32_bf16 v[66:69], v[122:125], v[138:141], v[66:69]
	v_mfma_f32_16x16x32_bf16 v[54:57], v[114:117], v[156:159], v[54:57]
	v_mfma_f32_16x16x32_bf16 v[50:53], v[122:125], v[156:159], v[50:53]
	v_mfma_f32_16x16x32_bf16 v[86:89], v[118:121], v[134:137], v[86:89]
	v_mfma_f32_16x16x32_bf16 v[82:85], v[126:129], v[134:137], v[82:85]
	v_mfma_f32_16x16x32_bf16 v[70:73], v[118:121], v[152:155], v[70:73]
	v_mfma_f32_16x16x32_bf16 v[66:69], v[126:129], v[152:155], v[66:69]
	v_mfma_f32_16x16x32_bf16 v[54:57], v[118:121], v[160:163], v[54:57]
	v_mfma_f32_16x16x32_bf16 v[50:53], v[126:129], v[160:163], v[50:53]
	s_barrier
	s_setprio 1
	s_mov_b32 m0, s29
	v_lshl_add_u64 v[164:165], s[22:23], 0, v[0:1]
	s_add_u32 s62, s22, 0x80000
	s_addc_u32 s63, s23, 0
	ds_read_b128 v[130:133], v167 offset:16384
	ds_read_b128 v[134:137], v167 offset:17408
	ds_read_b128 v[138:141], v167 offset:18432
	ds_read_b128 v[152:155], v167 offset:19456
	ds_read_b128 v[156:159], v167 offset:20480
	ds_read_b128 v[160:163], v167 offset:21504
	s_cmp_lg_u32 s100, 0
	s_cbranch_scc1 .Ltl_ou_0s
	global_load_lds_dwordx4 v0, s[22:23]
	v_lshl_add_u64 v[168:169], s[22:23], 0, v[146:147]
	s_mov_b32 m0, s30
	s_nop 0
	global_load_lds_dwordx4 v146, s[22:23]
	s_mov_b32 m0, s33
	v_lshl_add_u64 v[172:173], s[24:25], 0, v[144:145]
	global_load_lds_dwordx4 v0, s[62:63]
	s_mov_b32 m0, s34
	s_nop 0
	global_load_lds_dwordx4 v146, s[62:63]
	v_lshl_add_u64 v[170:171], s[24:25], 0, v[142:143]
	s_mov_b32 m0, s35
	s_nop 0
	global_load_lds_dwordx4 v142, s[24:25]
	s_mov_b32 m0, s36
	s_nop 0
	s_and_b64 vcc, exec, s[10:11]
	s_cbranch_vccz .Lnm3o_skip1
	global_load_lds_dwordx4 v144, s[24:25]
	s_waitcnt vmcnt(8)
	s_branch .Lnm3o_done1

; #define PG8_STAGE(bufoff, gbase, voff) do { _Pragma("unroll") for (int _i = 0; _i < 2; ++_i) \
;         __builtin_amdgcn_global_load_lds((const unsigned*)((const char*)(gbase) + (voff)[_i]), (LAS unsigned*)(lds + (bufoff) + ldsw + _i * 8192), 16, 0, 0); } while (0)
; #define PG8_LDA(dst, b, h) do { _Pragma("unroll") for (int m = 0; m < NM; ++m) _Pragma("unroll") for (int k = 0; k < 2; ++k) dst[m][k] = *(const LAS bf16x8*)(lds + PG8_SA(b, h) + aoff + m * 2048 + k * 1024); } while (0)
; #define PG8_LDB(dst, b, h) do { _Pragma("unroll") for (int n = 0; n < 2; ++n) _Pragma("unroll") for (int k = 0; k < 2; ++k) dst[n][k] = *(const LAS bf16x8*)(lds + PG8_SB(b, h) + boff + n * 2048 + k * 1024); } while (0)
; #define PG8_MMA(ai, bj, At, Bt) do { __builtin_amdgcn_s_setprio(1); _Pragma("unroll") for (int m = 0; m < NM; ++m) _Pragma("unroll") for (int n = 0; n < 2; ++n) _Pragma("unroll") for (int k = 0; k < 2; ++k) \
;         acc[ai][bj][m][n] = __builtin_amdgcn_mfma_f32_16x16x32_bf16(Bt[n][k], At[m][k], acc[ai][bj][m][n], 0, 0, 0); __builtin_amdgcn_s_setprio(0); } while (0)
; #define PG8_WAIT_V(n) asm volatile("s_waitcnt vmcnt(" #n ")" ::: "memory")
; #define PG8_WAIT_L(n) asm volatile("s_waitcnt lgkmcnt(" #n ")" ::: "memory")
; #define PG8_BAR __builtin_amdgcn_s_barrier()
; #define PG8_SCHED __builtin_amdgcn_sched_barrier(0)
;     ...
;             PG8_WAIT_V(8); PG8_WAIT_L(0); PG8_BAR; PG8_MMA(1, 0, At, B0); PG8_MMA(1, 1, At, B1); PG8_BAR; PG8_SCHED;
;             PG8_LDB(B0, 1, 0); PG8_LDB(B1, 1, 1); PG8_SCHED; PG8_LDA(At, 1, 0); PG8_STAGE(PG8_SA(0, 1), a2 + hstepA, voffA);
.Ltl_ou_0d:
	s_waitcnt lgkmcnt(0)
	s_setprio 0
	s_barrier
	v_mfma_f32_16x16x32_bf16 v[46:49], v[90:93], v[130:133], v[46:49]
	v_mfma_f32_16x16x32_bf16 v[42:45], v[98:101], v[130:133], v[42:45]
	v_mfma_f32_16x16x32_bf16 v[30:33], v[90:93], v[138:141], v[30:33]
	v_mfma_f32_16x16x32_bf16 v[26:29], v[98:101], v[138:141], v[26:29]
	v_mfma_f32_16x16x32_bf16 v[14:17], v[90:93], v[156:159], v[14:17]
	v_mfma_f32_16x16x32_bf16 v[10:13], v[98:101], v[156:159], v[10:13]
	v_mfma_f32_16x16x32_bf16 v[46:49], v[94:97], v[134:137], v[46:49]
	v_mfma_f32_16x16x32_bf16 v[42:45], v[102:105], v[134:137], v[42:45]
	v_mfma_f32_16x16x32_bf16 v[30:33], v[94:97], v[152:155], v[30:33]
	v_mfma_f32_16x16x32_bf16 v[26:29], v[102:105], v[152:155], v[26:29]
	v_mfma_f32_16x16x32_bf16 v[14:17], v[94:97], v[160:163], v[14:17]
	v_mfma_f32_16x16x32_bf16 v[10:13], v[102:105], v[160:163], v[10:13]
	v_mfma_f32_16x16x32_bf16 v[38:41], v[114:117], v[130:133], v[38:41]
	v_mfma_f32_16x16x32_bf16 v[34:37], v[122:125], v[130:133], v[34:37]
	v_mfma_f32_16x16x32_bf16 v[22:25], v[114:117], v[138:141], v[22:25]
	v_mfma_f32_16x16x32_bf16 v[18:21], v[122:125], v[138:141], v[18:21]
	v_mfma_f32_16x16x32_bf16 v[6:9], v[114:117], v[156:159], v[6:9]
	v_mfma_f32_16x16x32_bf16 v[2:5], v[122:125], v[156:159], v[2:5]
	v_mfma_f32_16x16x32_bf16 v[38:41], v[118:121], v[134:137], v[38:41]
	v_mfma_f32_16x16x32_bf16 v[34:37], v[126:129], v[134:137], v[34:37]
	v_mfma_f32_16x16x32_bf16 v[22:25], v[118:121], v[152:155], v[22:25]
	v_mfma_f32_16x16x32_bf16 v[18:21], v[126:129], v[152:155], v[18:21]
	v_mfma_f32_16x16x32_bf16 v[6:9], v[118:121], v[160:163], v[6:9]
	v_mfma_f32_16x16x32_bf16 v[2:5], v[126:129], v[160:163], v[2:5]
	s_barrier
	s_setprio 1
	v_add_u32_e32 v102, s40, v166
	v_add_u32_e32 v126, s45, v166
	ds_read_b128 v[90:93], v102
	ds_read_b128 v[94:97], v102 offset:1024
	ds_read_b128 v[98:101], v102 offset:2048
	ds_read_b128 v[102:105], v102 offset:3072
	ds_read_b128 v[114:117], v126
	ds_read_b128 v[118:121], v126 offset:1024
	ds_read_b128 v[122:125], v126 offset:2048
	ds_read_b128 v[126:129], v126 offset:3072
	s_add_u32 s24, s24, 0x60000
	s_addc_u32 s25, s25, 0
	s_mov_b32 m0, s37
	ds_read_b128 v[130:133], v167 offset:32768
	ds_read_b128 v[134:137], v167 offset:33792
	ds_read_b128 v[138:141], v167 offset:34816
	ds_read_b128 v[152:155], v167 offset:35840
	ds_read_b128 v[156:159], v167 offset:36864
	ds_read_b128 v[160:163], v167 offset:37888
	s_cmp_lg_u32 s100, 0
	s_cbranch_scc1 .Ltl_ou_1s
	global_load_lds_dwordx4 v142, s[24:25]
	s_mov_b32 m0, s38
	s_nop 0
	s_and_b64 vcc, exec, s[10:11]
	s_cbranch_vccz .Lnm3o_skip2
	global_load_lds_dwordx4 v144, s[24:25]
	s_waitcnt vmcnt(8)
	s_branch .Lnm3o_done2

; #define PG8_STAGE(bufoff, gbase, voff) do { _Pragma("unroll") for (int _i = 0; _i < 2; ++_i) \
;         __builtin_amdgcn_global_load_lds((const unsigned*)((const char*)(gbase) + (voff)[_i]), (LAS unsigned*)(lds + (bufoff) + ldsw + _i * 8192), 16, 0, 0); } while (0)
; #define PG8_LDA(dst, b, h) do { _Pragma("unroll") for (int m = 0; m < NM; ++m) _Pragma("unroll") for (int k = 0; k < 2; ++k) dst[m][k] = *(const LAS bf16x8*)(lds + PG8_SA(b, h) + aoff + m * 2048 + k * 1024); } while (0)
; #define PG8_MMA(ai, bj, At, Bt) do { __builtin_amdgcn_s_setprio(1); _Pragma("unroll") for (int m = 0; m < NM; ++m) _Pragma("unroll") for (int n = 0; n < 2; ++n) _Pragma("unroll") for (int k = 0; k < 2; ++k) \
;         acc[ai][bj][m][n] = __builtin_amdgcn_mfma_f32_16x16x32_bf16(Bt[n][k], At[m][k], acc[ai][bj][m][n], 0, 0, 0); __builtin_amdgcn_s_setprio(0); } while (0)
; #define PG8_WAIT_V(n) asm volatile("s_waitcnt vmcnt(" #n ")" ::: "memory")
; #define PG8_WAIT_L(n) asm volatile("s_waitcnt lgkmcnt(" #n ")" ::: "memory")
; #define PG8_BAR __builtin_amdgcn_s_barrier()
; #define PG8_SCHED __builtin_amdgcn_sched_barrier(0)
;     ...
;             PG8_WAIT_V(8); PG8_WAIT_L(0); PG8_BAR; PG8_MMA(0, 0, At, B0); PG8_MMA(0, 1, At, B1); PG8_BAR; PG8_SCHED;
;             PG8_LDA(At, 1, 1); PG8_STAGE(PG8_SB(1, 0), b3, voffB); PG8_STAGE(PG8_SB(1, 1), b3 + hstepB, voffB); PG8_STAGE(PG8_SA(1, 0), a3, voffA);
.Ltl_ou_1d:
	s_waitcnt lgkmcnt(0)
	s_setprio 0
	s_barrier
	v_mfma_f32_16x16x32_bf16 v[110:113], v[90:93], v[130:133], v[110:113]
	v_mfma_f32_16x16x32_bf16 v[106:109], v[98:101], v[130:133], v[106:109]
	v_mfma_f32_16x16x32_bf16 v[78:81], v[90:93], v[138:141], v[78:81]
	v_mfma_f32_16x16x32_bf16 v[74:77], v[98:101], v[138:141], v[74:77]
	v_mfma_f32_16x16x32_bf16 v[62:65], v[90:93], v[156:159], v[62:65]
	v_mfma_f32_16x16x32_bf16 v[58:61], v[98:101], v[156:159], v[58:61]
	v_mfma_f32_16x16x32_bf16 v[110:113], v[94:97], v[134:137], v[110:113]
	v_mfma_f32_16x16x32_bf16 v[106:109], v[102:105], v[134:137], v[106:109]
	v_mfma_f32_16x16x32_bf16 v[78:81], v[94:97], v[152:155], v[78:81]
	v_mfma_f32_16x16x32_bf16 v[74:77], v[102:105], v[152:155], v[74:77]
	v_mfma_f32_16x16x32_bf16 v[62:65], v[94:97], v[160:163], v[62:65]
	v_mfma_f32_16x16x32_bf16 v[58:61], v[102:105], v[160:163], v[58:61]
	v_mfma_f32_16x16x32_bf16 v[86:89], v[114:117], v[130:133], v[86:89]
	v_mfma_f32_16x16x32_bf16 v[82:85], v[122:125], v[130:133], v[82:85]
	v_mfma_f32_16x16x32_bf16 v[70:73], v[114:117], v[138:141], v[70:73]
	v_mfma_f32_16x16x32_bf16 v[66:69], v[122:125], v[138:141], v[66:69]
	v_mfma_f32_16x16x32_bf16 v[54:57], v[114:117], v[156:159], v[54:57]
	v_mfma_f32_16x16x32_bf16 v[50:53], v[122:125], v[156:159], v[50:53]
	v_mfma_f32_16x16x32_bf16 v[86:89], v[118:121], v[134:137], v[86:89]
	v_mfma_f32_16x16x32_bf16 v[82:85], v[126:129], v[134:137], v[82:85]
	v_mfma_f32_16x16x32_bf16 v[70:73], v[118:121], v[152:155], v[70:73]
	v_mfma_f32_16x16x32_bf16 v[66:69], v[126:129], v[152:155], v[66:69]
	v_mfma_f32_16x16x32_bf16 v[54:57], v[118:121], v[160:163], v[54:57]
	v_mfma_f32_16x16x32_bf16 v[50:53], v[126:129], v[160:163], v[50:53]
	s_barrier
	s_setprio 1
	s_mov_b32 m0, s41
	v_lshl_add_u64 v[164:165], v[164:165], 0, s[66:67]
	s_add_u32 s22, s22, 0x80080
	s_addc_u32 s23, s23, 0
	ds_read_b128 v[130:133], v167 offset:49152
	ds_read_b128 v[134:137], v167 offset:50176
	ds_read_b128 v[138:141], v167 offset:51200
	ds_read_b128 v[152:155], v167 offset:52224
	ds_read_b128 v[156:159], v167 offset:53248
	ds_read_b128 v[160:163], v167 offset:54272
	s_cmp_lg_u32 s100, 0
	s_cbranch_scc1 .Ltl_ou_2s
	global_load_lds_dwordx4 v[164:165], off
	v_lshl_add_u64 v[164:165], v[168:169], 0, s[66:67]
	s_mov_b32 m0, s42
	s_nop 0
	global_load_lds_dwordx4 v[164:165], off
	s_mov_b32 m0, s46
	s_nop 0
	global_load_lds_dwordx4 v0, s[22:23]
	s_mov_b32 m0, s47
	s_nop 0
	global_load_lds_dwordx4 v146, s[22:23]
	v_lshl_add_u64 v[164:165], v[170:171], 0, s[66:67]
	s_mov_b32 m0, s43
	s_nop 0
	global_load_lds_dwordx4 v[164:165], off
	v_lshl_add_u64 v[164:165], v[172:173], 0, s[66:67]
	s_mov_b32 m0, s44
	s_nop 0
	s_and_b64 vcc, exec, s[10:11]
	s_cbranch_vccz .Lnm3o_skip3
	global_load_lds_dwordx4 v[164:165], off
	s_waitcnt vmcnt(8)
	s_branch .Lnm3o_done3

; #define PG8_MMA(ai, bj, At, Bt) do { __builtin_amdgcn_s_setprio(1); _Pragma("unroll") for (int m = 0; m < NM; ++m) _Pragma("unroll") for (int n = 0; n < 2; ++n) _Pragma("unroll") for (int k = 0; k < 2; ++k) \
;         acc[ai][bj][m][n] = __builtin_amdgcn_mfma_f32_16x16x32_bf16(Bt[n][k], At[m][k], acc[ai][bj][m][n], 0, 0, 0); __builtin_amdgcn_s_setprio(0); } while (0)
; #define PG8_WAIT_V(n) asm volatile("s_waitcnt vmcnt(" #n ")" ::: "memory")
; #define PG8_WAIT_L(n) asm volatile("s_waitcnt lgkmcnt(" #n ")" ::: "memory")
; #define PG8_BAR __builtin_amdgcn_s_barrier()
; #define PG8_SCHED __builtin_amdgcn_sched_barrier(0)
;     ...
;             PG8_WAIT_V(8); PG8_WAIT_L(0); PG8_BAR; PG8_MMA(1, 0, At, B0); PG8_MMA(1, 1, At, B1); PG8_BAR; PG8_SCHED;
;     ...
;         }
;         if constexpr (ALIGN_EPI) { if (wr == 0) PG8_BAR; }
.Ltl_ou_2d:
	s_waitcnt lgkmcnt(0)
	s_setprio 0
	s_barrier
	v_mfma_f32_16x16x32_bf16 v[46:49], v[90:93], v[130:133], v[46:49]
	v_mfma_f32_16x16x32_bf16 v[42:45], v[98:101], v[130:133], v[42:45]
	v_mfma_f32_16x16x32_bf16 v[30:33], v[90:93], v[138:141], v[30:33]
	v_mfma_f32_16x16x32_bf16 v[26:29], v[98:101], v[138:141], v[26:29]
	v_mfma_f32_16x16x32_bf16 v[14:17], v[90:93], v[156:159], v[14:17]
	v_mfma_f32_16x16x32_bf16 v[10:13], v[98:101], v[156:159], v[10:13]
	v_mfma_f32_16x16x32_bf16 v[46:49], v[94:97], v[134:137], v[46:49]
	v_mfma_f32_16x16x32_bf16 v[42:45], v[102:105], v[134:137], v[42:45]
	v_mfma_f32_16x16x32_bf16 v[30:33], v[94:97], v[152:155], v[30:33]
	v_mfma_f32_16x16x32_bf16 v[26:29], v[102:105], v[152:155], v[26:29]
	v_mfma_f32_16x16x32_bf16 v[14:17], v[94:97], v[160:163], v[14:17]
	v_mfma_f32_16x16x32_bf16 v[10:13], v[102:105], v[160:163], v[10:13]
	v_mfma_f32_16x16x32_bf16 v[38:41], v[114:117], v[130:133], v[38:41]
	v_mfma_f32_16x16x32_bf16 v[34:37], v[122:125], v[130:133], v[34:37]
	v_mfma_f32_16x16x32_bf16 v[22:25], v[114:117], v[138:141], v[22:25]
	v_mfma_f32_16x16x32_bf16 v[18:21], v[122:125], v[138:141], v[18:21]
	v_mfma_f32_16x16x32_bf16 v[6:9], v[114:117], v[156:159], v[6:9]
	v_mfma_f32_16x16x32_bf16 v[2:5], v[122:125], v[156:159], v[2:5]
	v_mfma_f32_16x16x32_bf16 v[38:41], v[118:121], v[134:137], v[38:41]
	v_mfma_f32_16x16x32_bf16 v[34:37], v[126:129], v[134:137], v[34:37]
	v_mfma_f32_16x16x32_bf16 v[22:25], v[118:121], v[152:155], v[22:25]
	v_mfma_f32_16x16x32_bf16 v[18:21], v[126:129], v[152:155], v[18:21]
	v_mfma_f32_16x16x32_bf16 v[6:9], v[118:121], v[160:163], v[6:9]
	v_mfma_f32_16x16x32_bf16 v[2:5], v[126:129], v[160:163], v[2:5]
	s_barrier
	s_setprio 1
	s_add_i32 s59, s59, 2
	s_add_u32 s8, s8, 0x100
	s_addc_u32 s9, s9, 0
	s_add_u32 s15, s15, 0x100
	s_addc_u32 s58, s58, 0
	s_cmp_gt_u32 s59, 29
	s_cbranch_scc0 .LBB0_1650
	s_setprio 0
	s_and_b64 vcc, exec, s[10:11]
	s_cbranch_vccz .LBB0_1653
	s_barrier

; #define PG8_STAGE(bufoff, gbase, voff) do { _Pragma("unroll") for (int _i = 0; _i < 2; ++_i) \
;         __builtin_amdgcn_global_load_lds((const unsigned*)((const char*)(gbase) + (voff)[_i]), (LAS unsigned*)(lds + (bufoff) + ldsw + _i * 8192), 16, 0, 0); } while (0)
; #define PG8_LDA(dst, b, h) do { _Pragma("unroll") for (int m = 0; m < NM; ++m) _Pragma("unroll") for (int k = 0; k < 2; ++k) dst[m][k] = *(const LAS bf16x8*)(lds + PG8_SA(b, h) + aoff + m * 2048 + k * 1024); } while (0)
; #define PG8_MMA(ai, bj, At, Bt) do { __builtin_amdgcn_s_setprio(1); _Pragma("unroll") for (int m = 0; m < NM; ++m) _Pragma("unroll") for (int n = 0; n < 2; ++n) _Pragma("unroll") for (int k = 0; k < 2; ++k) \
;         acc[ai][bj][m][n] = __builtin_amdgcn_mfma_f32_16x16x32_bf16(Bt[n][k], At[m][k], acc[ai][bj][m][n], 0, 0, 0); __builtin_amdgcn_s_setprio(0); } while (0)
; #define PG8_WAIT_V(n) asm volatile("s_waitcnt vmcnt(" #n ")" ::: "memory")
; #define PG8_WAIT_L(n) asm volatile("s_waitcnt lgkmcnt(" #n ")" ::: "memory")
; #define PG8_BAR __builtin_amdgcn_s_barrier()
; #define PG8_SCHED __builtin_amdgcn_sched_barrier(0)
;     ...
;             PG8_WAIT_V(8); PG8_WAIT_L(0); PG8_BAR; PG8_MMA(0, 0, At, B0); PG8_MMA(0, 1, At, B1); PG8_BAR; PG8_SCHED;
;             PG8_LDA(At, 0, 1); PG8_STAGE(PG8_SB(0, 0), b2, voffB); PG8_STAGE(PG8_SB(0, 1), b2 + hstepB, voffB); PG8_STAGE(PG8_SA(0, 0), a2, voffA);
.Lnm3d_done0:
	s_waitcnt lgkmcnt(0)
	s_setprio 0
	s_barrier
	v_mfma_f32_16x16x32_bf16 v[110:113], v[90:93], v[130:133], v[110:113]
	v_mfma_f32_16x16x32_bf16 v[106:109], v[98:101], v[130:133], v[106:109]
	v_mfma_f32_16x16x32_bf16 v[78:81], v[90:93], v[138:141], v[78:81]
	v_mfma_f32_16x16x32_bf16 v[74:77], v[98:101], v[138:141], v[74:77]
	v_mfma_f32_16x16x32_bf16 v[62:65], v[90:93], v[156:159], v[62:65]
	v_mfma_f32_16x16x32_bf16 v[58:61], v[98:101], v[156:159], v[58:61]
	v_mfma_f32_16x16x32_bf16 v[110:113], v[94:97], v[134:137], v[110:113]
	v_mfma_f32_16x16x32_bf16 v[106:109], v[102:105], v[134:137], v[106:109]
	v_mfma_f32_16x16x32_bf16 v[78:81], v[94:97], v[152:155], v[78:81]
	v_mfma_f32_16x16x32_bf16 v[74:77], v[102:105], v[152:155], v[74:77]
	v_mfma_f32_16x16x32_bf16 v[62:65], v[94:97], v[160:163], v[62:65]
	v_mfma_f32_16x16x32_bf16 v[58:61], v[102:105], v[160:163], v[58:61]
	v_mfma_f32_16x16x32_bf16 v[86:89], v[114:117], v[130:133], v[86:89]
	v_mfma_f32_16x16x32_bf16 v[82:85], v[122:125], v[130:133], v[82:85]
	v_mfma_f32_16x16x32_bf16 v[70:73], v[114:117], v[138:141], v[70:73]
	v_mfma_f32_16x16x32_bf16 v[66:69], v[122:125], v[138:141], v[66:69]
	v_mfma_f32_16x16x32_bf16 v[54:57], v[114:117], v[156:159], v[54:57]
	v_mfma_f32_16x16x32_bf16 v[50:53], v[122:125], v[156:159], v[50:53]
	v_mfma_f32_16x16x32_bf16 v[86:89], v[118:121], v[134:137], v[86:89]
	v_mfma_f32_16x16x32_bf16 v[82:85], v[126:129], v[134:137], v[82:85]
	v_mfma_f32_16x16x32_bf16 v[70:73], v[118:121], v[152:155], v[70:73]
	v_mfma_f32_16x16x32_bf16 v[66:69], v[126:129], v[152:155], v[66:69]
	v_mfma_f32_16x16x32_bf16 v[54:57], v[118:121], v[160:163], v[54:57]
	v_mfma_f32_16x16x32_bf16 v[50:53], v[126:129], v[160:163], v[50:53]
	s_barrier
	s_setprio 1
	s_mov_b32 m0, s27
	v_lshl_add_u64 v[164:165], s[18:19], 0, v[0:1]
	s_add_u32 s14, s18, 0x160000
	s_addc_u32 s15, s19, 0
	ds_read_b128 v[130:133], v167 offset:16384
	ds_read_b128 v[134:137], v167 offset:17408
	ds_read_b128 v[138:141], v167 offset:18432
	ds_read_b128 v[152:155], v167 offset:19456
	ds_read_b128 v[156:159], v167 offset:20480
	ds_read_b128 v[160:163], v167 offset:21504
	s_cmp_lg_u32 s100, 0
	s_cbranch_scc1 .Ltl_dn_0s
	global_load_lds_dwordx4 v0, s[18:19]
	v_lshl_add_u64 v[168:169], s[18:19], 0, v[146:147]
	s_mov_b32 m0, s28
	s_nop 0
	global_load_lds_dwordx4 v146, s[18:19]
	s_mov_b32 m0, s30
	v_lshl_add_u64 v[172:173], s[20:21], 0, v[144:145]
	global_load_lds_dwordx4 v0, s[14:15]
	s_mov_b32 m0, s31
	s_nop 0
	global_load_lds_dwordx4 v146, s[14:15]
	v_lshl_add_u64 v[170:171], s[20:21], 0, v[142:143]
	s_mov_b32 m0, s34
	s_nop 0
	global_load_lds_dwordx4 v142, s[20:21]
	s_mov_b32 m0, s35
	s_nop 0
	s_and_b64 vcc, exec, s[8:9]
	s_cbranch_vccz .Lnm3d_skip1
	global_load_lds_dwordx4 v144, s[20:21]
	s_waitcnt vmcnt(8)
	s_branch .Lnm3d_done1

; #define PG8_STAGE(bufoff, gbase, voff) do { _Pragma("unroll") for (int _i = 0; _i < 2; ++_i) \
;         __builtin_amdgcn_global_load_lds((const unsigned*)((const char*)(gbase) + (voff)[_i]), (LAS unsigned*)(lds + (bufoff) + ldsw + _i * 8192), 16, 0, 0); } while (0)
; #define PG8_LDA(dst, b, h) do { _Pragma("unroll") for (int m = 0; m < NM; ++m) _Pragma("unroll") for (int k = 0; k < 2; ++k) dst[m][k] = *(const LAS bf16x8*)(lds + PG8_SA(b, h) + aoff + m * 2048 + k * 1024); } while (0)
; #define PG8_LDB(dst, b, h) do { _Pragma("unroll") for (int n = 0; n < 2; ++n) _Pragma("unroll") for (int k = 0; k < 2; ++k) dst[n][k] = *(const LAS bf16x8*)(lds + PG8_SB(b, h) + boff + n * 2048 + k * 1024); } while (0)
; #define PG8_MMA(ai, bj, At, Bt) do { __builtin_amdgcn_s_setprio(1); _Pragma("unroll") for (int m = 0; m < NM; ++m) _Pragma("unroll") for (int n = 0; n < 2; ++n) _Pragma("unroll") for (int k = 0; k < 2; ++k) \
;         acc[ai][bj][m][n] = __builtin_amdgcn_mfma_f32_16x16x32_bf16(Bt[n][k], At[m][k], acc[ai][bj][m][n], 0, 0, 0); __builtin_amdgcn_s_setprio(0); } while (0)
; #define PG8_WAIT_V(n) asm volatile("s_waitcnt vmcnt(" #n ")" ::: "memory")
; #define PG8_WAIT_L(n) asm volatile("s_waitcnt lgkmcnt(" #n ")" ::: "memory")
; #define PG8_BAR __builtin_amdgcn_s_barrier()
; #define PG8_SCHED __builtin_amdgcn_sched_barrier(0)
;     ...
;             PG8_WAIT_V(8); PG8_WAIT_L(0); PG8_BAR; PG8_MMA(1, 0, At, B0); PG8_MMA(1, 1, At, B1); PG8_BAR; PG8_SCHED;
;             PG8_LDB(B0, 1, 0); PG8_LDB(B1, 1, 1); PG8_SCHED; PG8_LDA(At, 1, 0); PG8_STAGE(PG8_SA(0, 1), a2 + hstepA, voffA);
.Ltl_dn_0d:
	s_waitcnt lgkmcnt(0)
	s_setprio 0
	s_barrier
	v_mfma_f32_16x16x32_bf16 v[46:49], v[90:93], v[130:133], v[46:49]
	v_mfma_f32_16x16x32_bf16 v[42:45], v[98:101], v[130:133], v[42:45]
	v_mfma_f32_16x16x32_bf16 v[30:33], v[90:93], v[138:141], v[30:33]
	v_mfma_f32_16x16x32_bf16 v[26:29], v[98:101], v[138:141], v[26:29]
	v_mfma_f32_16x16x32_bf16 v[14:17], v[90:93], v[156:159], v[14:17]
	v_mfma_f32_16x16x32_bf16 v[10:13], v[98:101], v[156:159], v[10:13]
	v_mfma_f32_16x16x32_bf16 v[46:49], v[94:97], v[134:137], v[46:49]
	v_mfma_f32_16x16x32_bf16 v[42:45], v[102:105], v[134:137], v[42:45]
	v_mfma_f32_16x16x32_bf16 v[30:33], v[94:97], v[152:155], v[30:33]
	v_mfma_f32_16x16x32_bf16 v[26:29], v[102:105], v[152:155], v[26:29]
	v_mfma_f32_16x16x32_bf16 v[14:17], v[94:97], v[160:163], v[14:17]
	v_mfma_f32_16x16x32_bf16 v[10:13], v[102:105], v[160:163], v[10:13]
	v_mfma_f32_16x16x32_bf16 v[38:41], v[114:117], v[130:133], v[38:41]
	v_mfma_f32_16x16x32_bf16 v[34:37], v[122:125], v[130:133], v[34:37]
	v_mfma_f32_16x16x32_bf16 v[22:25], v[114:117], v[138:141], v[22:25]
	v_mfma_f32_16x16x32_bf16 v[18:21], v[122:125], v[138:141], v[18:21]
	v_mfma_f32_16x16x32_bf16 v[6:9], v[114:117], v[156:159], v[6:9]
	v_mfma_f32_16x16x32_bf16 v[2:5], v[122:125], v[156:159], v[2:5]
	v_mfma_f32_16x16x32_bf16 v[38:41], v[118:121], v[134:137], v[38:41]
	v_mfma_f32_16x16x32_bf16 v[34:37], v[126:129], v[134:137], v[34:37]
	v_mfma_f32_16x16x32_bf16 v[22:25], v[118:121], v[152:155], v[22:25]
	v_mfma_f32_16x16x32_bf16 v[18:21], v[126:129], v[152:155], v[18:21]
	v_mfma_f32_16x16x32_bf16 v[6:9], v[118:121], v[160:163], v[6:9]
	v_mfma_f32_16x16x32_bf16 v[2:5], v[126:129], v[160:163], v[2:5]
	s_barrier
	s_setprio 1
	v_add_u32_e32 v102, s38, v166
	v_add_u32_e32 v126, s45, v166
	ds_read_b128 v[90:93], v102
	ds_read_b128 v[94:97], v102 offset:1024
	ds_read_b128 v[98:101], v102 offset:2048
	ds_read_b128 v[102:105], v102 offset:3072
	ds_read_b128 v[114:117], v126
	ds_read_b128 v[118:121], v126 offset:1024
	ds_read_b128 v[122:125], v126 offset:2048
	ds_read_b128 v[126:129], v126 offset:3072
	s_add_u32 s14, s20, 0x108000
	s_addc_u32 s15, s21, 0
	s_mov_b32 m0, s36
	ds_read_b128 v[130:133], v167 offset:32768
	ds_read_b128 v[134:137], v167 offset:33792
	ds_read_b128 v[138:141], v167 offset:34816
	ds_read_b128 v[152:155], v167 offset:35840
	ds_read_b128 v[156:159], v167 offset:36864
	ds_read_b128 v[160:163], v167 offset:37888
	s_cmp_lg_u32 s100, 0
	s_cbranch_scc1 .Ltl_dn_1s
	global_load_lds_dwordx4 v142, s[14:15]
	s_mov_b32 m0, s37
	s_nop 0
	s_and_b64 vcc, exec, s[8:9]
	s_cbranch_vccz .Lnm3d_skip2
	global_load_lds_dwordx4 v144, s[14:15]
	s_waitcnt vmcnt(8)
	s_branch .Lnm3d_done2

; #define PG8_STAGE(bufoff, gbase, voff) do { _Pragma("unroll") for (int _i = 0; _i < 2; ++_i) \
;         __builtin_amdgcn_global_load_lds((const unsigned*)((const char*)(gbase) + (voff)[_i]), (LAS unsigned*)(lds + (bufoff) + ldsw + _i * 8192), 16, 0, 0); } while (0)
; #define PG8_LDA(dst, b, h) do { _Pragma("unroll") for (int m = 0; m < NM; ++m) _Pragma("unroll") for (int k = 0; k < 2; ++k) dst[m][k] = *(const LAS bf16x8*)(lds + PG8_SA(b, h) + aoff + m * 2048 + k * 1024); } while (0)
; #define PG8_MMA(ai, bj, At, Bt) do { __builtin_amdgcn_s_setprio(1); _Pragma("unroll") for (int m = 0; m < NM; ++m) _Pragma("unroll") for (int n = 0; n < 2; ++n) _Pragma("unroll") for (int k = 0; k < 2; ++k) \
;         acc[ai][bj][m][n] = __builtin_amdgcn_mfma_f32_16x16x32_bf16(Bt[n][k], At[m][k], acc[ai][bj][m][n], 0, 0, 0); __builtin_amdgcn_s_setprio(0); } while (0)
; #define PG8_WAIT_V(n) asm volatile("s_waitcnt vmcnt(" #n ")" ::: "memory")
; #define PG8_WAIT_L(n) asm volatile("s_waitcnt lgkmcnt(" #n ")" ::: "memory")
; #define PG8_BAR __builtin_amdgcn_s_barrier()
; #define PG8_SCHED __builtin_amdgcn_sched_barrier(0)
;     ...
;             PG8_WAIT_V(8); PG8_WAIT_L(0); PG8_BAR; PG8_MMA(0, 0, At, B0); PG8_MMA(0, 1, At, B1); PG8_BAR; PG8_SCHED;
;             PG8_LDA(At, 1, 1); PG8_STAGE(PG8_SB(1, 0), b3, voffB); PG8_STAGE(PG8_SB(1, 1), b3 + hstepB, voffB); PG8_STAGE(PG8_SA(1, 0), a3, voffA);
.Ltl_dn_1d:
	s_waitcnt lgkmcnt(0)
	s_setprio 0
	s_barrier
	v_mfma_f32_16x16x32_bf16 v[110:113], v[90:93], v[130:133], v[110:113]
	v_mfma_f32_16x16x32_bf16 v[106:109], v[98:101], v[130:133], v[106:109]
	v_mfma_f32_16x16x32_bf16 v[78:81], v[90:93], v[138:141], v[78:81]
	v_mfma_f32_16x16x32_bf16 v[74:77], v[98:101], v[138:141], v[74:77]
	v_mfma_f32_16x16x32_bf16 v[62:65], v[90:93], v[156:159], v[62:65]
	v_mfma_f32_16x16x32_bf16 v[58:61], v[98:101], v[156:159], v[58:61]
	v_mfma_f32_16x16x32_bf16 v[110:113], v[94:97], v[134:137], v[110:113]
	v_mfma_f32_16x16x32_bf16 v[106:109], v[102:105], v[134:137], v[106:109]
	v_mfma_f32_16x16x32_bf16 v[78:81], v[94:97], v[152:155], v[78:81]
	v_mfma_f32_16x16x32_bf16 v[74:77], v[102:105], v[152:155], v[74:77]
	v_mfma_f32_16x16x32_bf16 v[62:65], v[94:97], v[160:163], v[62:65]
	v_mfma_f32_16x16x32_bf16 v[58:61], v[102:105], v[160:163], v[58:61]
	v_mfma_f32_16x16x32_bf16 v[86:89], v[114:117], v[130:133], v[86:89]
	v_mfma_f32_16x16x32_bf16 v[82:85], v[122:125], v[130:133], v[82:85]
	v_mfma_f32_16x16x32_bf16 v[70:73], v[114:117], v[138:141], v[70:73]
	v_mfma_f32_16x16x32_bf16 v[66:69], v[122:125], v[138:141], v[66:69]
	v_mfma_f32_16x16x32_bf16 v[54:57], v[114:117], v[156:159], v[54:57]
	v_mfma_f32_16x16x32_bf16 v[50:53], v[122:125], v[156:159], v[50:53]
	v_mfma_f32_16x16x32_bf16 v[86:89], v[118:121], v[134:137], v[86:89]
	v_mfma_f32_16x16x32_bf16 v[82:85], v[126:129], v[134:137], v[82:85]
	v_mfma_f32_16x16x32_bf16 v[70:73], v[118:121], v[152:155], v[70:73]
	v_mfma_f32_16x16x32_bf16 v[66:69], v[126:129], v[152:155], v[66:69]
	v_mfma_f32_16x16x32_bf16 v[54:57], v[118:121], v[160:163], v[54:57]
	v_mfma_f32_16x16x32_bf16 v[50:53], v[126:129], v[160:163], v[50:53]
	s_barrier
	s_setprio 1
	s_mov_b32 m0, s41
	v_lshl_add_u64 v[164:165], v[164:165], 0, s[66:67]
	s_add_u32 s14, s18, 0x160080
	s_addc_u32 s15, s19, 0
	ds_read_b128 v[130:133], v167 offset:49152
	ds_read_b128 v[134:137], v167 offset:50176
	ds_read_b128 v[138:141], v167 offset:51200
	ds_read_b128 v[152:155], v167 offset:52224
	ds_read_b128 v[156:159], v167 offset:53248
	ds_read_b128 v[160:163], v167 offset:54272
	s_cmp_lg_u32 s100, 0
	s_cbranch_scc1 .Ltl_dn_2s
	global_load_lds_dwordx4 v[164:165], off
	v_lshl_add_u64 v[164:165], v[168:169], 0, s[66:67]
	s_mov_b32 m0, s42
	s_nop 0
	global_load_lds_dwordx4 v[164:165], off
	s_mov_b32 m0, s46
	s_nop 0
	global_load_lds_dwordx4 v0, s[14:15]
	s_mov_b32 m0, s47
	s_nop 0
	global_load_lds_dwordx4 v146, s[14:15]
	v_lshl_add_u64 v[164:165], v[170:171], 0, s[66:67]
	s_mov_b32 m0, s43
	s_nop 0
	global_load_lds_dwordx4 v[164:165], off
	v_lshl_add_u64 v[164:165], v[172:173], 0, s[66:67]
	s_mov_b32 m0, s44
	s_nop 0
	s_and_b64 vcc, exec, s[8:9]
	s_cbranch_vccz .Lnm3d_skip3
	global_load_lds_dwordx4 v[164:165], off
	s_waitcnt vmcnt(8)
	s_branch .Lnm3d_done3

; #define PG8_MMA(ai, bj, At, Bt) do { __builtin_amdgcn_s_setprio(1); _Pragma("unroll") for (int m = 0; m < NM; ++m) _Pragma("unroll") for (int n = 0; n < 2; ++n) _Pragma("unroll") for (int k = 0; k < 2; ++k) \
;         acc[ai][bj][m][n] = __builtin_amdgcn_mfma_f32_16x16x32_bf16(Bt[n][k], At[m][k], acc[ai][bj][m][n], 0, 0, 0); __builtin_amdgcn_s_setprio(0); } while (0)
; #define PG8_WAIT_V(n) asm volatile("s_waitcnt vmcnt(" #n ")" ::: "memory")
; #define PG8_WAIT_L(n) asm volatile("s_waitcnt lgkmcnt(" #n ")" ::: "memory")
; #define PG8_BAR __builtin_amdgcn_s_barrier()
; #define PG8_SCHED __builtin_amdgcn_sched_barrier(0)
;     ...
;             PG8_WAIT_V(8); PG8_WAIT_L(0); PG8_BAR; PG8_MMA(1, 0, At, B0); PG8_MMA(1, 1, At, B1); PG8_BAR; PG8_SCHED;
;     ...
;         }
;         if constexpr (ALIGN_EPI) { if (wr == 0) PG8_BAR; }
.Ltl_dn_2d:
	s_waitcnt lgkmcnt(0)
	s_setprio 0
	s_barrier
	v_mfma_f32_16x16x32_bf16 v[46:49], v[90:93], v[130:133], v[46:49]
	v_mfma_f32_16x16x32_bf16 v[42:45], v[98:101], v[130:133], v[42:45]
	v_mfma_f32_16x16x32_bf16 v[30:33], v[90:93], v[138:141], v[30:33]
	v_mfma_f32_16x16x32_bf16 v[26:29], v[98:101], v[138:141], v[26:29]
	v_mfma_f32_16x16x32_bf16 v[14:17], v[90:93], v[156:159], v[14:17]
	v_mfma_f32_16x16x32_bf16 v[10:13], v[98:101], v[156:159], v[10:13]
	v_mfma_f32_16x16x32_bf16 v[46:49], v[94:97], v[134:137], v[46:49]
	v_mfma_f32_16x16x32_bf16 v[42:45], v[102:105], v[134:137], v[42:45]
	v_mfma_f32_16x16x32_bf16 v[30:33], v[94:97], v[152:155], v[30:33]
	v_mfma_f32_16x16x32_bf16 v[26:29], v[102:105], v[152:155], v[26:29]
	v_mfma_f32_16x16x32_bf16 v[14:17], v[94:97], v[160:163], v[14:17]
	v_mfma_f32_16x16x32_bf16 v[10:13], v[102:105], v[160:163], v[10:13]
	v_mfma_f32_16x16x32_bf16 v[38:41], v[114:117], v[130:133], v[38:41]
	v_mfma_f32_16x16x32_bf16 v[34:37], v[122:125], v[130:133], v[34:37]
	v_mfma_f32_16x16x32_bf16 v[22:25], v[114:117], v[138:141], v[22:25]
	v_mfma_f32_16x16x32_bf16 v[18:21], v[122:125], v[138:141], v[18:21]
	v_mfma_f32_16x16x32_bf16 v[6:9], v[114:117], v[156:159], v[6:9]
	v_mfma_f32_16x16x32_bf16 v[2:5], v[122:125], v[156:159], v[2:5]
	v_mfma_f32_16x16x32_bf16 v[38:41], v[118:121], v[134:137], v[38:41]
	v_mfma_f32_16x16x32_bf16 v[34:37], v[126:129], v[134:137], v[34:37]
	v_mfma_f32_16x16x32_bf16 v[22:25], v[118:121], v[152:155], v[22:25]
	v_mfma_f32_16x16x32_bf16 v[18:21], v[126:129], v[152:155], v[18:21]
	v_mfma_f32_16x16x32_bf16 v[6:9], v[118:121], v[160:163], v[6:9]
	v_mfma_f32_16x16x32_bf16 v[2:5], v[126:129], v[160:163], v[2:5]
	s_barrier
	s_setprio 1
	s_add_i32 s60, s60, 2
	s_add_u32 s2, s2, 0x100
	s_addc_u32 s3, s3, 0
	s_cmpk_gt_u32 s60, 0x55
	s_mov_b64 s[14:15], s[16:17]
	s_cbranch_scc0 .LBB0_2158
	s_setprio 0
	s_and_b64 vcc, exec, s[8:9]
	s_cbranch_vccz .LBB0_2161
	s_barrier
